# speedup vs baseline: 1.0066x; 1.0066x over previous
; __device__ __forceinline__ int tid_() { int t = threadIdx.x; asm volatile("" : "+v"(t)); return t; }
; __device__ __forceinline__ void phase_final(float* x, const float* g, int bid, int nb) {
;   const int tidn = tid_();
;   int wid = tidn >> 6, lane = tidn & 63;
;   for (int r = bid * 8 + wid; r < T_ALL; r += nb * 8) {
;     float* xr = x + (long)r * D;
;     float4 v[4];
;     float ss = 0.f;
; #pragma unroll
;     for (int i = 0; i < 4; ++i) {
;       v[i] = *(const float4*)(xr + i * 256 + lane * 4);
;       ss += v[i].x * v[i].x + v[i].y * v[i].y + v[i].z * v[i].z + v[i].w * v[i].w;
;     }
; #pragma unroll
;     for (int o = 32; o >= 1; o >>= 1) ss += shfl_xor_l(ss, lane, o);
;     float rinv = rsqrtf(ss * (1.0f / D) + EPS);
; #pragma unroll
;     for (int i = 0; i < 4; ++i) {
;       float4 gg = *(const float4*)(g + i * 256 + lane * 4);
;       float4 o = make_float4(v[i].x * rinv * gg.x, v[i].y * rinv * gg.y, v[i].z * rinv * gg.z, v[i].w * rinv * gg.w);
;       *(float4*)(xr + i * 256 + lane * 4) = o;
;     }
;   }
.LBB0_13:
	global_load_dwordx4 v[12:15], v[4:5], off
	global_load_dwordx4 v[16:19], v[2:3], off
	global_load_dwordx4 v[20:23], v[4:5], off offset:1024
	global_load_dwordx4 v[208:211], v[4:5], off offset:2048
	global_load_dwordx4 v[212:215], v[4:5], off offset:3072
	global_load_dwordx4 v[196:199], v[2:3], off offset:1024
	global_load_dwordx4 v[200:203], v[2:3], off offset:2048
	global_load_dwordx4 v[204:207], v[2:3], off offset:3072
	v_add_u32_e32 v6, s62, v6
	s_mov_b32 s10, 0x13fff
	s_waitcnt vmcnt(0)
	v_mov_b32_e32 v26, v13
	v_mov_b32_e32 v24, v12
	s_waitcnt vmcnt(0)
	v_mov_b32_e32 v27, v21
	v_mov_b32_e32 v25, v20
	v_pk_mul_f32 v[26:27], v[26:27], v[26:27]
	v_mov_b32_e32 v28, v15
	v_pk_fma_f32 v[24:25], v[24:25], v[24:25], v[26:27]
	v_mov_b32_e32 v26, v14
	v_mov_b32_e32 v27, v22
	v_mov_b32_e32 v29, v23
	v_pk_fma_f32 v[24:25], v[26:27], v[26:27], v[24:25]
	s_nop 0
	v_pk_fma_f32 v[32:33], v[28:29], v[28:29], v[24:25]
	v_mov_b64_e32 v[24:25], v[208:209]
	v_mov_b64_e32 v[26:27], v[210:211]
	v_mov_b64_e32 v[28:29], v[212:213]
	v_mov_b64_e32 v[30:31], v[214:215]
	v_add_f32_e32 v32, v32, v33
	s_waitcnt vmcnt(1)
	v_mov_b32_e32 v36, v25
	s_waitcnt vmcnt(0)
	v_mov_b32_e32 v37, v29
	v_mov_b32_e32 v34, v24
	v_mov_b32_e32 v35, v28
	v_pk_mul_f32 v[36:37], v[36:37], v[36:37]
	v_mov_b32_e32 v38, v27
	v_pk_fma_f32 v[34:35], v[34:35], v[34:35], v[36:37]
	v_mov_b32_e32 v36, v26
	v_mov_b32_e32 v37, v30
	v_mov_b32_e32 v39, v31
	v_pk_fma_f32 v[34:35], v[36:37], v[36:37], v[34:35]
	s_nop 0
	v_pk_fma_f32 v[34:35], v[38:39], v[38:39], v[34:35]
	s_nop 0
	v_add_f32_e32 v32, v32, v34
	v_add_f32_e32 v32, v32, v35
	ds_bpermute_b32 v33, v0, v32
	s_waitcnt lgkmcnt(0)
	v_add_f32_e32 v32, v32, v33
	ds_bpermute_b32 v33, v7, v32
	s_waitcnt lgkmcnt(0)
	v_add_f32_e32 v32, v32, v33
	ds_bpermute_b32 v33, v8, v32
	s_waitcnt lgkmcnt(0)
	v_add_f32_e32 v32, v32, v33
	ds_bpermute_b32 v33, v9, v32
	s_waitcnt lgkmcnt(0)
	v_add_f32_e32 v32, v32, v33
	ds_bpermute_b32 v33, v10, v32
	s_waitcnt lgkmcnt(0)
	v_add_f32_e32 v32, v32, v33
	ds_bpermute_b32 v33, v11, v32
	s_waitcnt lgkmcnt(0)
	v_add_f32_e32 v32, v32, v33
	v_fmamk_f32 v32, v32, 0x3a800000, v183
	v_cmp_gt_f32_e32 vcc, s18, v32
	v_mul_f32_e32 v33, 0x4b800000, v32
	s_nop 0
	v_cndmask_b32_e32 v32, v32, v33, vcc
	v_rsq_f32_e32 v32, v32
	s_nop 0
	v_mul_f32_e32 v33, 0x45800000, v32
	v_cndmask_b32_e32 v32, v32, v33, vcc
	v_pk_mul_f32 v[12:13], v[12:13], v[32:33] op_sel_hi:[1,0]
	v_pk_mul_f32 v[14:15], v[14:15], v[32:33] op_sel_hi:[1,0]
	v_pk_mul_f32 v[12:13], v[16:17], v[12:13]
	v_pk_mul_f32 v[14:15], v[18:19], v[14:15]
	global_store_dwordx4 v[4:5], v[12:15], off nt
	s_nop 1
	v_mov_b64_e32 v[12:13], v[196:197]
	v_mov_b64_e32 v[14:15], v[198:199]
	v_pk_mul_f32 v[16:17], v[20:21], v[32:33] op_sel_hi:[1,0]
	v_cmp_lt_i32_e32 vcc, s10, v6
	s_or_b64 s[8:9], vcc, s[8:9]
	s_nop 0
	v_pk_mul_f32 v[12:13], v[12:13], v[16:17]
	v_pk_mul_f32 v[16:17], v[22:23], v[32:33] op_sel_hi:[1,0]
	s_nop 0
	v_pk_mul_f32 v[14:15], v[14:15], v[16:17]
	global_store_dwordx4 v[4:5], v[12:15], off offset:1024 nt
	s_nop 1
	v_mov_b64_e32 v[12:13], v[200:201]
	v_mov_b64_e32 v[14:15], v[202:203]
	v_pk_mul_f32 v[16:17], v[24:25], v[32:33] op_sel_hi:[1,0]
	s_nop 0
	v_pk_mul_f32 v[12:13], v[16:17], v[12:13]
	v_pk_mul_f32 v[16:17], v[26:27], v[32:33] op_sel_hi:[1,0]
	s_nop 0
	v_pk_mul_f32 v[14:15], v[16:17], v[14:15]
	global_store_dwordx4 v[4:5], v[12:15], off offset:2048 nt
	s_nop 1
	v_mov_b64_e32 v[12:13], v[204:205]
	v_mov_b64_e32 v[14:15], v[206:207]
	v_pk_mul_f32 v[16:17], v[28:29], v[32:33] op_sel_hi:[1,0]
	s_nop 0
	v_pk_mul_f32 v[12:13], v[16:17], v[12:13]
	v_pk_mul_f32 v[16:17], v[30:31], v[32:33] op_sel_hi:[1,0]
	s_nop 0
	v_pk_mul_f32 v[14:15], v[16:17], v[14:15]
	global_store_dwordx4 v[4:5], v[12:15], off offset:3072 nt
	v_lshl_add_u64 v[4:5], v[4:5], 0, s[16:17]
	s_andn2_b64 exec, exec, s[8:9]
	s_cbranch_execnz .LBB0_13
